# K-loop head placed on a 64-byte boundary (on top of static priority raise and duplicate-wait removal)
# speedup vs baseline: 1.0046x; 1.0046x over previous
.Lprio_lo:
	.p2align	6
